# adaLN layer 3 on the first 64 scan-2 idle CUs (they take 24 conversion items per wave, the other 64 take 50), prologue: adaLN layers 0-2 on CUs 0-191 while CUs 192-255 convert w_in[0]
# baseline (speedup 1.0000x reference)
; DI void phase_prologue(const Frame& F0, const Args& a) {
;     ...
;         for (int unit = F.vcu; unit < DEPTH * 64; unit += F.G) {
;             const int li = unit >> 6, cb = unit & 63, n0 = cb * 192;
.LBB0_19:
	s_or_b64 exec, exec, s[0:1]
	s_mov_b32 s89, s24
	s_movk_i32 s4, 0xff
	s_cmp_lg_u32 s98, 0
	s_cbranch_scc1 .Lada_lim
	s_cmp_eq_u32 s3, 0x100
	s_cselect_b32 s4, 191, s4

; #define LAS __attribute__((address_space(3)))
; DI void phase_prologue(const Frame& F0, const Args& a) {
;     ...
;         LAS float* scr = (LAS float*)(F.lds + 43008 + F.wave * 8448);
;         const int gw = F.vcu * NWAVES + F.wave, NGW = F.G * NWAVES;
;         constexpr int I_IN = 32 * (GIN / 32), I_SQ = 32 * 64, I_GU = 32 * (2 * DFF / 32), I_DN = (DFF / 64) * 64;
;         constexpr int NITEMS = 2 * I_IN + 2 * I_SQ + 2 * I_SQ + DEPTH * I_GU + DEPTH * I_DN;
;         for (int it = gw; it < NITEMS; it += NGW) {
.LBB0_79:
	s_or_b64 exec, exec, s[8:9]
	s_lshl_b32 s0, s60, 3
	s_add_i32 s6, s0, s44
	s_cmp_gt_i32 s6, 0x1583f
	s_cbranch_scc1 .LBB0_11
	s_mov_b32 s90, s6
	s_mov_b32 s92, 0
	s_mov_b32 s91, 0x15840
	v_readlane_b32 s93, v252, 53
	s_cmp_eq_u32 s3, 0x100
	s_cbranch_scc0 .Lconv_entry
	s_mov_b32 s92, 1
	s_mov_b32 s91, 0x1820
	s_cmp_lt_u32 s60, 0xc0
	s_cbranch_scc1 .Lconv_exit
	s_sub_u32 s90, s90, 0x600
	s_movk_i32 s93, 0x200

; DI void phase_prologue(const Frame& F0, const Args& a) {
;     ...
;         const int gw = F.vcu * NWAVES + F.wave, NGW = F.G * NWAVES;
;         constexpr int I_IN = 32 * (GIN / 32), I_SQ = 32 * 64, I_GU = 32 * (2 * DFF / 32), I_DN = (DFF / 64) * 64;
;         constexpr int NITEMS = 2 * I_IN + 2 * I_SQ + 2 * I_SQ + DEPTH * I_GU + DEPTH * I_DN;
;         for (int it = gw; it < NITEMS; it += NGW) {
.Lconv_exit:
	s_cmp_eq_u32 s92, 3
	s_cbranch_scc0 .Lcx_std
	s_cmp_eq_u32 s91, 0x9400
	s_cbranch_scc1 .Lcx_std
	v_readlane_b32 s1, v252, 48
	s_lshr_b32 s4, s1, 5
	s_lshl_b32 s4, s4, 4
	s_and_b32 s5, s1, 15
	s_or_b32 s4, s4, s5
	s_cmp_lt_u32 s4, 64
	s_cbranch_scc1 .Lcx_std
	s_sub_u32 s4, s4, 64
	s_lshl_b32 s4, s4, 3
	s_add_i32 s4, s4, s44
	s_add_i32 s90, s4, 0x6000
	s_movk_i32 s93, 0x200
	s_mov_b32 s91, 0x9400
	v_mov_b32_e32 v78, v222
	s_cmp_lt_i32 s90, s91
	s_cbranch_scc1 .Lconv_entry

; DI void phase_prologue(const Frame& F0, const Args& a) {
;     ...
;         const int gw = F.vcu * NWAVES + F.wave, NGW = F.G * NWAVES;
;         constexpr int I_IN = 32 * (GIN / 32), I_SQ = 32 * 64, I_GU = 32 * (2 * DFF / 32), I_DN = (DFF / 64) * 64;
;         constexpr int NITEMS = 2 * I_IN + 2 * I_SQ + 2 * I_SQ + DEPTH * I_GU + DEPTH * I_DN;
;         for (int it = gw; it < NITEMS; it += NGW) {
; DI void phase_scan(const Frame& F0, const Args& a, int colmajor) {
;     ...
;     for (int it = F.vcu; it < 256; it += F.G) {
;         if ((it & 31) >= 16) continue;
.Lada_hook_ret:
	s_mov_b32 s98, 0
	v_readlane_b32 s0, v255, 17
	v_readlane_b32 s1, v252, 48
	v_readlane_b32 s44, v252, 49
	v_readlane_b32 s86, v252, 46
	v_readlane_b32 s87, v252, 47
	v_mov_b32_e32 v78, v222
	s_lshr_b32 s4, s1, 5
	s_lshl_b32 s4, s4, 4
	s_and_b32 s5, s1, 15
	s_or_b32 s4, s4, s5
	s_cmp_ge_u32 s44, 8
	s_cbranch_scc1 .Lconv_ret_scan
	s_mul_i32 s4, s4, 8
	s_add_i32 s90, s4, s44
	s_movk_i32 s93, 0x400
	s_mov_b32 s4, 0xac20
	s_mov_b32 s5, 0x6000
	s_cmp_eq_u32 s0, 0
	s_cselect_b32 s92, 2, 3
	s_cselect_b32 s91, s4, s5
	s_cmp_lt_i32 s90, s91
	s_cbranch_scc1 .Lconv_entry
